# v38 + in-proj GEMM epilogue: per-row RMS scales hoisted into the tile prologue (de-serialised epilogue)
# baseline (speedup 1.0000x reference)
; DI float rowscale(const float* ss, int R) {
;   const float4* q = (const float4*)(ss + (size_t)R * 16);
;   float4 a = q[0], b = q[1], c = q[2], d = q[3];
;   float t = ((a.x + a.y) + (a.z + a.w)) + ((b.x + b.y) + (b.z + b.w)) + ((c.x + c.y) + (c.z + c.w)) + ((d.x + d.y) + (d.z + d.w));
;   return rsqrtf(t * (1.f / 1024.f) + 1e-6f);
; template <int MODE, bool SWAP, int MT>
; DI void gemm_tile(const int wv_, const Params& p, const u16* __restrict__ A, const u16* __restrict__ Bt, int brow, int bcol, char* smem, const float* gnext) {
;     ...
;   const int tid = tid_, wid = tid >> 6, lane = tid & 63, wr = wid >> 1, wc = wid & 1, fr = lane & 15, fq = lane >> 4;
;   f32x4 acc[MT][4];
; #pragma unroll
;   for (int m = 0; m < MT; ++m)
; #pragma unroll
;     for (int n = 0; n < 4; ++n) acc[m][n] = f32x4{0.f, 0.f, 0.f, 0.f};
;   const int ra = tid >> 2, cb = (tid & 3) * 8;
;   const u16* ga0 = A + (size_t)(brow + ra) * 1024 + cb;
;   const u16* ga1 = A + (size_t)(brow + 128 + ra) * 1024 + cb;
;   const u16* gb0 = Bt + (size_t)(bcol + ra) * 1024 + cb;
;   auto stage = [&](int t, int buf) {
;     char* sA = smem + buf * 24576; char* sB = sA + 16384;
;     if (MT >= 2 || tid < 256) __builtin_amdgcn_global_load_lds((const unsigned*)(ga0 + t * 32), (unsigned*)(sA + tid * 16), 16, 0, 0);
;     if (MT == 4) __builtin_amdgcn_global_load_lds((const unsigned*)(ga1 + t * 32), (unsigned*)(sA + 8192 + tid * 16), 16, 0, 0);
;     __builtin_amdgcn_global_load_lds((const unsigned*)(gb0 + t * 32), (unsigned*)(sB + tid * 16), 16, 0, 0);
;   };
;   stage(0, 0);
.LBB0_84:
	s_mul_hi_i32 s0, s14, 0x92492493
	s_add_i32 s0, s0, s14
	s_lshr_b32 s1, s0, 31
	s_ashr_i32 s0, s0, 4
	s_add_i32 s19, s0, s1
	s_mul_i32 s0, s19, 0xffffffe4
	s_add_i32 s0, s0, s14
	s_and_b32 s1, s0, -4
	s_lshl_b32 s18, s19, 8
	s_lshl_b32 s15, s0, 7
	s_cmp_lg_u32 s1, 20
	s_mov_b64 s[0:1], -1
	s_mulk_i32 s19, 0xe00
	s_cbranch_scc0 .LBB0_88
	s_mov_b32 s1, 0
	v_readlane_b32 s20, v127, 0
	v_mbcnt_lo_u32_b32 v0, -1, s1
	v_mbcnt_hi_u32_b32 v0, -1, v0
	v_add_u32_e32 v12, s33, v0
	s_mov_b32 s1, s16
	v_ashrrev_i32_e32 v13, 2, v12
	v_add_u32_e32 v0, s18, v13
	s_mov_b32 s1, s17
	v_ashrrev_i32_e32 v1, 31, v0
	v_lshlrev_b64 v[4:5], 11, v[0:1]
	v_readlane_b32 s21, v127, 1
	v_lshlrev_b32_e32 v76, 4, v12
	v_and_b32_e32 v2, 48, v76
	v_lshl_add_u64 v[6:7], s[20:21], 0, v[4:5]
	v_add_u32_e32 v0, 0x80, v0
	v_readfirstlane_b32 s1, v76
	v_lshl_add_u64 v[6:7], v[6:7], 0, v[2:3]
	v_ashrrev_i32_e32 v1, 31, v0
	s_mov_b32 m0, s1
	v_lshlrev_b64 v[8:9], 11, v[0:1]
	global_load_lds_dwordx4 v[6:7], off
	v_add_u32_e32 v6, 0x2000, v76
	v_lshl_add_u64 v[0:1], s[20:21], 0, v[8:9]
	v_add_u32_e32 v10, s15, v13
	v_readfirstlane_b32 s1, v6
	v_lshl_add_u64 v[0:1], v[0:1], 0, v[2:3]
	v_ashrrev_i32_e32 v11, 31, v10
	s_mov_b32 m0, s1
	v_lshlrev_b64 v[10:11], 11, v[10:11]
	global_load_lds_dwordx4 v[0:1], off
	v_add_u32_e32 v0, 0x4000, v76
	v_lshl_add_u64 v[10:11], s[2:3], 0, v[10:11]
	v_readfirstlane_b32 s1, v0
	v_lshl_add_u64 v[10:11], v[10:11], 0, v[2:3]
	s_mov_b32 m0, s1
	v_and_b32_e32 v74, 15, v12
	global_load_lds_dwordx4 v[10:11], off
	v_readlane_b32 s20, v127, 22
	v_bfe_u32 v72, v12, 6, 1
	v_ashrrev_i32_e32 v73, 7, v12
	v_lshlrev_b32_e32 v0, 6, v74
	v_or_b32_e32 v4, v4, v2
	v_readlane_b32 s21, v127, 23
	v_lshl_or_b32 v78, v72, 12, v0
	v_lshl_or_b32 v79, v73, 12, v0
	v_lshl_add_u64 v[0:1], s[20:21], 0, v[4:5]
	v_add_u32_e32 v4, s12, v13
	v_subrev_u32_e32 v4, s19, v4
	v_ashrrev_i32_e32 v5, 31, v4
	v_lshlrev_b64 v[4:5], 11, v[4:5]
	v_or_b32_e32 v4, v4, v2
	v_bfe_u32 v75, v12, 4, 2
	v_or_b32_e32 v8, v8, v2
	v_lshl_add_u64 v[70:71], s[4:5], 0, v[4:5]
	v_mov_b32_e32 v4, 0
	s_mov_b32 s0, 0
	v_lshlrev_b32_e32 v77, 4, v75
	v_lshl_add_u64 v[68:69], s[20:21], 0, v[8:9]
	v_mov_b32_e32 v5, v4
	v_mov_b32_e32 v6, v4
	v_mov_b32_e32 v7, v4
	v_mov_b32_e32 v8, v4
	v_mov_b32_e32 v9, v4
	v_mov_b32_e32 v10, v4
	v_mov_b32_e32 v11, v4
	v_mov_b32_e32 v12, v4
	v_mov_b32_e32 v13, v4
	v_mov_b32_e32 v14, v4
	v_mov_b32_e32 v15, v4
	v_mov_b32_e32 v16, v4
	v_mov_b32_e32 v17, v4
	v_mov_b32_e32 v18, v4
	v_mov_b32_e32 v19, v4
	v_mov_b32_e32 v20, v4
	v_mov_b32_e32 v21, v4
	v_mov_b32_e32 v22, v4
	v_mov_b32_e32 v23, v4
	v_mov_b32_e32 v24, v4
	v_mov_b32_e32 v25, v4
	v_mov_b32_e32 v26, v4
	v_mov_b32_e32 v27, v4
	v_mov_b32_e32 v28, v4
	v_mov_b32_e32 v29, v4
	v_mov_b32_e32 v30, v4
	v_mov_b32_e32 v31, v4
	v_mov_b32_e32 v32, v4
	v_mov_b32_e32 v33, v4
	v_mov_b32_e32 v34, v4
	v_mov_b32_e32 v35, v4
	v_mov_b32_e32 v44, v4
	v_mov_b32_e32 v45, v4
	v_mov_b32_e32 v46, v4
	v_mov_b32_e32 v47, v4
	v_mov_b32_e32 v36, v4
	v_mov_b32_e32 v37, v4
	v_mov_b32_e32 v38, v4
	v_mov_b32_e32 v39, v4
	v_mov_b32_e32 v40, v4
	v_mov_b32_e32 v41, v4
	v_mov_b32_e32 v42, v4
	v_mov_b32_e32 v43, v4
	v_mov_b32_e32 v48, v4
	v_mov_b32_e32 v49, v4
	v_mov_b32_e32 v50, v4
	v_mov_b32_e32 v51, v4
	v_mov_b32_e32 v52, v4
	v_mov_b32_e32 v53, v4
	v_mov_b32_e32 v54, v4
	v_mov_b32_e32 v55, v4
	v_mov_b32_e32 v56, v4
	v_mov_b32_e32 v57, v4
	v_mov_b32_e32 v58, v4
	v_mov_b32_e32 v59, v4
	v_mov_b32_e32 v60, v4
	v_mov_b32_e32 v61, v4
	v_mov_b32_e32 v62, v4
	v_mov_b32_e32 v63, v4
	v_mov_b32_e32 v64, v4
	v_mov_b32_e32 v65, v4
	v_mov_b32_e32 v66, v4
	v_mov_b32_e32 v67, v4
	v_readlane_b32 s22, v127, 2
	v_readlane_b32 s23, v127, 3
	v_or_b32_e32 v112, s18, v74
	v_lshl_add_u32 v112, v73, 6, v112
	v_lshlrev_b32_e32 v112, 6, v112
	global_load_dwordx4 v[4:7], v112, s[90:91]
	global_load_dwordx4 v[8:11], v112, s[90:91] offset:16
	global_load_dwordx4 v[12:15], v112, s[90:91] offset:32
	global_load_dwordx4 v[16:19], v112, s[90:91] offset:48
	global_load_dwordx4 v[20:23], v112, s[90:91] offset:1024
	global_load_dwordx4 v[24:27], v112, s[90:91] offset:1040
	global_load_dwordx4 v[28:31], v112, s[90:91] offset:1056
	global_load_dwordx4 v[32:35], v112, s[90:91] offset:1072
	global_load_dwordx4 v[36:39], v112, s[90:91] offset:2048
	global_load_dwordx4 v[40:43], v112, s[90:91] offset:2064
	global_load_dwordx4 v[44:47], v112, s[90:91] offset:2080
	global_load_dwordx4 v[48:51], v112, s[90:91] offset:2096
	global_load_dwordx4 v[52:55], v112, s[90:91] offset:3072
	global_load_dwordx4 v[56:59], v112, s[90:91] offset:3088
	global_load_dwordx4 v[60:63], v112, s[90:91] offset:3104
	global_load_dwordx4 v[64:67], v112, s[90:91] offset:3120
	v_mov_b32_e32 v113, 0x358637bd
	s_waitcnt vmcnt(0)
; DI float rowscale(const float* ss, int R) {
;   const float4* q = (const float4*)(ss + (size_t)R * 16);
;   float4 a = q[0], b = q[1], c = q[2], d = q[3];
;   float t = ((a.x + a.y) + (a.z + a.w)) + ((b.x + b.y) + (b.z + b.w)) + ((c.x + c.y) + (c.z + c.w)) + ((d.x + d.y) + (d.z + d.w));
;   return rsqrtf(t * (1.f / 1024.f) + 1e-6f);
; }
; template <int MODE, bool SWAP, int MT>
; DI void gemm_tile(const int wv_, const Params& p, const u16* __restrict__ A, const u16* __restrict__ Bt, int brow, int bcol, char* smem, const float* gnext) {
;     ...
;   f32x4 acc[MT][4];
; #pragma unroll
;   for (int m = 0; m < MT; ++m)
; #pragma unroll
;     for (int n = 0; n < 4; ++n) acc[m][n] = f32x4{0.f, 0.f, 0.f, 0.f};
	v_add_f32_e32 v108, v4, v5
	v_add_f32_e32 v108, v108, v6
	v_add_f32_e32 v108, v108, v7
	v_add_f32_e32 v108, v108, v8
	v_add_f32_e32 v108, v108, v9
	v_add_f32_e32 v108, v108, v10
	v_add_f32_e32 v108, v108, v11
	v_add_f32_e32 v108, v108, v12
	v_add_f32_e32 v108, v108, v13
	v_add_f32_e32 v108, v108, v14
	v_add_f32_e32 v108, v108, v15
	v_add_f32_e32 v108, v108, v16
	v_add_f32_e32 v108, v108, v17
	v_add_f32_e32 v108, v108, v18
	v_add_f32_e32 v108, v108, v19
	v_fmamk_f32 v108, v108, 0x3a800000, v113
	v_cmp_gt_f32_e32 vcc, s96, v108
	v_mul_f32_e32 v114, 0x4b800000, v108
	s_nop 0
	v_cndmask_b32_e32 v108, v108, v114, vcc
	v_rsq_f32_e32 v108, v108
	s_nop 0
	v_mul_f32_e32 v114, 0x45800000, v108
	v_cndmask_b32_e32 v108, v108, v114, vcc
	v_add_f32_e32 v109, v20, v21
	v_add_f32_e32 v109, v109, v22
	v_add_f32_e32 v109, v109, v23
	v_add_f32_e32 v109, v109, v24
	v_add_f32_e32 v109, v109, v25
	v_add_f32_e32 v109, v109, v26
	v_add_f32_e32 v109, v109, v27
	v_add_f32_e32 v109, v109, v28
	v_add_f32_e32 v109, v109, v29
	v_add_f32_e32 v109, v109, v30
	v_add_f32_e32 v109, v109, v31
	v_add_f32_e32 v109, v109, v32
	v_add_f32_e32 v109, v109, v33
	v_add_f32_e32 v109, v109, v34
	v_add_f32_e32 v109, v109, v35
	v_fmamk_f32 v109, v109, 0x3a800000, v113
	v_cmp_gt_f32_e32 vcc, s96, v109
	v_mul_f32_e32 v114, 0x4b800000, v109
	s_nop 0
	v_cndmask_b32_e32 v109, v109, v114, vcc
	v_rsq_f32_e32 v109, v109
	s_nop 0
	v_mul_f32_e32 v114, 0x45800000, v109
	v_cndmask_b32_e32 v109, v109, v114, vcc
	v_add_f32_e32 v110, v36, v37
	v_add_f32_e32 v110, v110, v38
	v_add_f32_e32 v110, v110, v39
	v_add_f32_e32 v110, v110, v40
	v_add_f32_e32 v110, v110, v41
	v_add_f32_e32 v110, v110, v42
	v_add_f32_e32 v110, v110, v43
	v_add_f32_e32 v110, v110, v44
	v_add_f32_e32 v110, v110, v45
	v_add_f32_e32 v110, v110, v46
	v_add_f32_e32 v110, v110, v47
	v_add_f32_e32 v110, v110, v48
	v_add_f32_e32 v110, v110, v49
	v_add_f32_e32 v110, v110, v50
	v_add_f32_e32 v110, v110, v51
	v_fmamk_f32 v110, v110, 0x3a800000, v113
	v_cmp_gt_f32_e32 vcc, s96, v110
	v_mul_f32_e32 v114, 0x4b800000, v110
	s_nop 0
	v_cndmask_b32_e32 v110, v110, v114, vcc
	v_rsq_f32_e32 v110, v110
	s_nop 0
	v_mul_f32_e32 v114, 0x45800000, v110
	v_cndmask_b32_e32 v110, v110, v114, vcc
	v_add_f32_e32 v111, v52, v53
	v_add_f32_e32 v111, v111, v54
	v_add_f32_e32 v111, v111, v55
	v_add_f32_e32 v111, v111, v56
	v_add_f32_e32 v111, v111, v57
	v_add_f32_e32 v111, v111, v58
	v_add_f32_e32 v111, v111, v59
	v_add_f32_e32 v111, v111, v60
	v_add_f32_e32 v111, v111, v61
	v_add_f32_e32 v111, v111, v62
	v_add_f32_e32 v111, v111, v63
	v_add_f32_e32 v111, v111, v64
	v_add_f32_e32 v111, v111, v65
	v_add_f32_e32 v111, v111, v66
	v_add_f32_e32 v111, v111, v67
	v_fmamk_f32 v111, v111, 0x3a800000, v113
	v_cmp_gt_f32_e32 vcc, s96, v111
	v_mul_f32_e32 v114, 0x4b800000, v111
	s_nop 0
	v_cndmask_b32_e32 v111, v111, v114, vcc
	v_rsq_f32_e32 v111, v111
	s_nop 0
	v_mul_f32_e32 v114, 0x45800000, v111
	v_cndmask_b32_e32 v111, v111, v114, vcc
	v_mov_b32_e32 v4, 0
	v_mov_b32_e32 v5, 0
	v_mov_b32_e32 v6, 0
	v_mov_b32_e32 v7, 0
	v_mov_b32_e32 v8, 0
	v_mov_b32_e32 v9, 0
	v_mov_b32_e32 v10, 0
	v_mov_b32_e32 v11, 0
	v_mov_b32_e32 v12, 0
	v_mov_b32_e32 v13, 0
	v_mov_b32_e32 v14, 0
	v_mov_b32_e32 v15, 0
	v_mov_b32_e32 v16, 0
	v_mov_b32_e32 v17, 0
	v_mov_b32_e32 v18, 0
	v_mov_b32_e32 v19, 0
	v_mov_b32_e32 v20, 0
	v_mov_b32_e32 v21, 0
	v_mov_b32_e32 v22, 0
	v_mov_b32_e32 v23, 0
	v_mov_b32_e32 v24, 0
	v_mov_b32_e32 v25, 0
	v_mov_b32_e32 v26, 0
	v_mov_b32_e32 v27, 0
	v_mov_b32_e32 v28, 0
	v_mov_b32_e32 v29, 0
	v_mov_b32_e32 v30, 0
	v_mov_b32_e32 v31, 0
	v_mov_b32_e32 v32, 0
	v_mov_b32_e32 v33, 0
	v_mov_b32_e32 v34, 0
	v_mov_b32_e32 v35, 0
	v_mov_b32_e32 v36, 0
	v_mov_b32_e32 v37, 0
	v_mov_b32_e32 v38, 0
	v_mov_b32_e32 v39, 0
	v_mov_b32_e32 v40, 0
	v_mov_b32_e32 v41, 0
	v_mov_b32_e32 v42, 0
	v_mov_b32_e32 v43, 0
	v_mov_b32_e32 v44, 0
	v_mov_b32_e32 v45, 0
	v_mov_b32_e32 v46, 0
	v_mov_b32_e32 v47, 0
	v_mov_b32_e32 v48, 0
	v_mov_b32_e32 v49, 0
	v_mov_b32_e32 v50, 0
	v_mov_b32_e32 v51, 0
	v_mov_b32_e32 v52, 0
	v_mov_b32_e32 v53, 0
	v_mov_b32_e32 v54, 0
	v_mov_b32_e32 v55, 0
	v_mov_b32_e32 v56, 0
	v_mov_b32_e32 v57, 0
	v_mov_b32_e32 v58, 0
	v_mov_b32_e32 v59, 0
	v_mov_b32_e32 v60, 0
	v_mov_b32_e32 v61, 0
	v_mov_b32_e32 v62, 0
	v_mov_b32_e32 v63, 0
	v_mov_b32_e32 v64, 0
	v_mov_b32_e32 v65, 0
	v_mov_b32_e32 v66, 0
	v_mov_b32_e32 v67, 0
; template <int MODE, bool SWAP, int MT>
; DI void gemm_tile(const int wv_, const Params& p, const u16* __restrict__ A, const u16* __restrict__ Bt, int brow, int bcol, char* smem, const float* gnext) {
;     ...
;   for (int t = 0; t < 32; ++t) {
;     asm volatile("s_waitcnt vmcnt(0)" ::: "memory");
;     __syncthreads();
;     if (t + 1 < 32) stage(t + 1, (t + 1) & 1);
;     const char* sA = smem + (t & 1) * 24576; const char* sB = sA + 16384;
;     bf16x8 Af[MT], Bf[4];
; #pragma unroll
;     for (int n = 0; n < 4; ++n) Bf[n] = *(const bf16x8*)(sB + (wc * 64 + n * 16 + fr) * 64 + fq * 16);
;     constexpr int MH = MT >= 2 ? MT / 2 : 1;
; #pragma unroll
;     for (int m = 0; m < MH; ++m) Af[m] = *(const bf16x8*)(sA + (wr * (16 * MT) + m * 16 + fr) * 64 + fq * 16);
;     __builtin_amdgcn_sched_barrier(0);
; #pragma unroll
;     for (int m = MH; m < MT; ++m) Af[m] = *(const bf16x8*)(sA + (wr * (16 * MT) + m * 16 + fr) * 64 + fq * 16);
; #pragma unroll
;     for (int m = 0; m < MH; ++m)
; #pragma unroll
;       for (int n = 0; n < 4; ++n)
;         acc[m][n] = SWAP ? __builtin_amdgcn_mfma_f32_16x16x32_bf16(Bf[n], Af[m], acc[m][n], 0, 0, 0)
;                          : __builtin_amdgcn_mfma_f32_16x16x32_bf16(Af[m], Bf[n], acc[m][n], 0, 0, 0);
;     __builtin_amdgcn_sched_barrier(0);
; #pragma unroll
;     for (int m = MH; m < MT; ++m)
; #pragma unroll
;       for (int n = 0; n < 4; ++n)
;         acc[m][n] = SWAP ? __builtin_amdgcn_mfma_f32_16x16x32_bf16(Bf[n], Af[m], acc[m][n], 0, 0, 0)
;                          : __builtin_amdgcn_mfma_f32_16x16x32_bf16(Af[m], Bf[n], acc[m][n], 0, 0, 0);
;   }
;   __syncthreads();
.LBB0_86:
	s_add_i32 s1, s0, 1
	s_bitcmp1_b32 s1, 0
	s_cselect_b32 s20, 0x6000, 0
	v_add_u32_e32 v2, s20, v76
	v_add_u32_e32 v80, 0x2000, v2
	v_readfirstlane_b32 s20, v2
	s_mov_b32 m0, s20
	v_readfirstlane_b32 s20, v80
	v_add_u32_e32 v2, 0x4000, v2
	s_waitcnt vmcnt(0)
	s_waitcnt vmcnt(0) lgkmcnt(0)
	s_barrier
	global_load_lds_dwordx4 v[0:1], off
	s_mov_b32 m0, s20
	v_readfirstlane_b32 s20, v2
	global_load_lds_dwordx4 v[68:69], off
	s_mov_b32 m0, s20
	s_bitcmp1_b32 s0, 0
	global_load_lds_dwordx4 v[70:71], off
	s_cselect_b32 s0, 0x6000, 0
	v_or_b32_e32 v2, s0, v77
	v_add_u32_e32 v92, v2, v78
	ds_read_b128 v[80:83], v92 offset:16384
	ds_read_b128 v[84:87], v92 offset:17408
	ds_read_b128 v[88:91], v92 offset:18432
	ds_read_b128 v[92:95], v92 offset:19456
	v_add_u32_e32 v2, v2, v79
	ds_read_b128 v[96:99], v2
	ds_read_b128 v[100:103], v2 offset:1024
	s_waitcnt lgkmcnt(0)
	v_mfma_f32_16x16x32_bf16 v[64:67], v[80:83], v[96:99], v[64:67]
	v_mfma_f32_16x16x32_bf16 v[60:63], v[84:87], v[96:99], v[60:63]
	v_mfma_f32_16x16x32_bf16 v[56:59], v[88:91], v[96:99], v[56:59]
	v_mfma_f32_16x16x32_bf16 v[52:55], v[92:95], v[96:99], v[52:55]
	ds_read_b128 v[96:99], v2 offset:2048
	ds_read_b128 v[104:107], v2 offset:3072
	v_mfma_f32_16x16x32_bf16 v[48:51], v[80:83], v[100:103], v[48:51]
	v_mfma_f32_16x16x32_bf16 v[40:43], v[84:87], v[100:103], v[40:43]
	v_mfma_f32_16x16x32_bf16 v[36:39], v[88:91], v[100:103], v[36:39]
	v_mfma_f32_16x16x32_bf16 v[44:47], v[92:95], v[100:103], v[44:47]
	s_waitcnt lgkmcnt(0)
	v_mfma_f32_16x16x32_bf16 v[32:35], v[80:83], v[96:99], v[32:35]
	v_lshl_add_u64 v[0:1], v[0:1], 0, 64
	v_lshl_add_u64 v[68:69], v[68:69], 0, 64
	v_lshl_add_u64 v[70:71], v[70:71], 0, 64
	v_mfma_f32_16x16x32_bf16 v[28:31], v[84:87], v[96:99], v[28:31]
	s_cmp_lg_u32 s1, 31
	s_mov_b32 s0, s1
	v_mfma_f32_16x16x32_bf16 v[24:27], v[88:91], v[96:99], v[24:27]
	v_mfma_f32_16x16x32_bf16 v[20:23], v[92:95], v[96:99], v[20:23]
	v_mfma_f32_16x16x32_bf16 v[16:19], v[80:83], v[104:107], v[16:19]
	v_mfma_f32_16x16x32_bf16 v[12:15], v[84:87], v[104:107], v[12:15]
	v_mfma_f32_16x16x32_bf16 v[8:11], v[88:91], v[104:107], v[8:11]
	v_mfma_f32_16x16x32_bf16 v[4:7], v[92:95], v[104:107], v[4:7]
	s_cbranch_scc1 .LBB0_86
	v_add_u32_e32 v0, v77, v79
	v_add_u32_e32 v1, v77, v78
	s_waitcnt vmcnt(0)
	s_waitcnt vmcnt(0)
	s_barrier
	ds_read_b128 v[68:71], v0 offset:25600
	ds_read_b128 v[80:83], v0 offset:24576
	ds_read_b128 v[76:79], v1 offset:44032
	ds_read_b128 v[84:87], v1 offset:43008
	ds_read_b128 v[88:91], v1 offset:41984
	ds_read_b128 v[92:95], v1 offset:40960
	s_waitcnt lgkmcnt(0)
	v_mfma_f32_16x16x32_bf16 v[64:67], v[92:95], v[80:83], v[64:67]
	v_mfma_f32_16x16x32_bf16 v[60:63], v[88:91], v[80:83], v[60:63]
	v_mfma_f32_16x16x32_bf16 v[56:59], v[84:87], v[80:83], v[56:59]
	v_mfma_f32_16x16x32_bf16 v[52:55], v[76:79], v[80:83], v[52:55]
	ds_read_b128 v[80:83], v0 offset:26624
	ds_read_b128 v[96:99], v0 offset:27648
	v_mfma_f32_16x16x32_bf16 v[48:51], v[92:95], v[68:71], v[48:51]
	v_mfma_f32_16x16x32_bf16 v[40:43], v[88:91], v[68:71], v[40:43]
	v_mfma_f32_16x16x32_bf16 v[36:39], v[84:87], v[68:71], v[36:39]
	v_mfma_f32_16x16x32_bf16 v[44:47], v[76:79], v[68:71], v[44:47]
	v_or_b32_e32 v0, s18, v74
	v_lshl_add_u32 v68, v73, 6, v0
	v_lshlrev_b32_e32 v0, 6, v72
	v_lshlrev_b32_e32 v1, 2, v75
	v_ashrrev_i32_e32 v69, 31, v68
	v_or3_b32 v70, v0, v1, s15
	v_lshlrev_b64 v[0:1], 6, v[68:69]
	v_lshl_add_u64 v[0:1], s[90:91], 0, v[0:1]
	s_waitcnt lgkmcnt(1)
	v_mfma_f32_16x16x32_bf16 v[32:35], v[92:95], v[80:83], v[32:35]
	s_waitcnt lgkmcnt(0)
	s_barrier
; DI unsigned pack2(float a, float b) { f32x2_t v = {a, b}; return __builtin_bit_cast(unsigned, __builtin_convertvector(v, bf16x2_t)); }
; template <int MODE, bool SWAP, int MT>
; DI void gemm_tile(const int wv_, const Params& p, const u16* __restrict__ A, const u16* __restrict__ Bt, int brow, int bcol, char* smem, const float* gnext) {
;     ...
;       } else {
;         const float rs = rowscale(p.ss, R);
; #pragma unroll
;         for (int n = 0; n < 4; ++n) { acc[m][n][0] *= rs; acc[m][n][1] *= rs; acc[m][n][2] *= rs; acc[m][n][3] *= rs; }
;         if (MODE == 0 && bcol >= 512 && bcol < 1536) {
;           int b = R / P, pos = R - b * P;
;           u16* dstb = (bcol < 1024 ? p.kc : p.vc);
; #pragma unroll
;           for (int n = 0; n < 4; ++n) {
;             int cc = (bcol & 511) + wc * 64 + n * 16 + fq * 4;
;             uint2 o; o.x = pack2(acc[m][n][0], acc[m][n][1]); o.y = pack2(acc[m][n][2], acc[m][n][3]);
;             *(uint2*)(dstb + ((size_t)((b * 8 + (cc >> 6)) * P + pos)) * 64 + (cc & 63)) = o;
;           }
;         } else {
;           const int LD = MODE == 0 ? LD_AB : LD_CD;
;           u16* pr = p.proj + (size_t)R * LD;
; #pragma unroll
;           for (int n = 0; n < 4; ++n) {
;             int col = bcol + wc * 64 + n * 16 + fq * 4;
;             if (MODE == 1 || col < 4184) {
;               uint2 o; o.x = pack2(acc[m][n][0], acc[m][n][1]); o.y = pack2(acc[m][n][2], acc[m][n][3]);
;               int pcol = (MODE == 0 && col >= 1536) ? col - 1024 : col;
;               *(uint2*)(pr + pcol) = o;
;               if (MODE == 0 && col >= 2560 && col < 2624) *(uint2*)(p.ikc + (size_t)R * 64 + (col - 2560)) = o;
;             }
;           }
	v_mfma_f32_16x16x32_bf16 v[28:31], v[88:91], v[80:83], v[28:31]
	v_mov_b32_e32 v69, 0x358637bd
	v_ashrrev_i32_e32 v71, 31, v70
	v_mfma_f32_16x16x32_bf16 v[24:27], v[84:87], v[80:83], v[24:27]
	v_mfma_f32_16x16x32_bf16 v[20:23], v[76:79], v[80:83], v[20:23]
	v_mfma_f32_16x16x32_bf16 v[8:11], v[84:87], v[96:99], v[8:11]
	v_mfma_f32_16x16x32_bf16 v[4:7], v[76:79], v[96:99], v[4:7]
	v_mfma_f32_16x16x32_bf16 v[12:15], v[88:91], v[96:99], v[12:15]
	v_mfma_f32_16x16x32_bf16 v[16:19], v[92:95], v[96:99], v[16:19]
	v_mov_b32_e32 v0, v108
	v_pk_mul_f32 v[72:73], v[64:65], v[0:1] op_sel_hi:[1,0]
	v_pk_mul_f32 v[66:67], v[66:67], v[0:1] op_sel_hi:[1,0]
	v_pk_mul_f32 v[64:65], v[60:61], v[0:1] op_sel_hi:[1,0]
	v_pk_mul_f32 v[62:63], v[62:63], v[0:1] op_sel_hi:[1,0]
	v_pk_mul_f32 v[60:61], v[56:57], v[0:1] op_sel_hi:[1,0]
	v_pk_mul_f32 v[58:59], v[58:59], v[0:1] op_sel_hi:[1,0]
	v_pk_mul_f32 v[56:57], v[52:53], v[0:1] op_sel_hi:[1,0]
	v_pk_mul_f32 v[54:55], v[54:55], v[0:1] op_sel_hi:[1,0]
	v_mov_b64_e32 v[0:1], s[68:69]
	v_mad_i64_i32 v[74:75], s[0:1], v68, s34, v[0:1]
	v_lshlrev_b64 v[52:53], 1, v[70:71]
	v_cvt_pk_bf16_f32 v56, v56, v57
	v_cvt_pk_bf16_f32 v57, v54, v55
	v_or_b32_e32 v54, 16, v68
	v_cvt_pk_bf16_f32 v72, v72, v73
	v_cvt_pk_bf16_f32 v73, v66, v67
	v_lshl_add_u64 v[66:67], v[74:75], 0, v[52:53]
	v_ashrrev_i32_e32 v55, 31, v54
	v_cvt_pk_bf16_f32 v64, v64, v65
	v_cvt_pk_bf16_f32 v65, v62, v63
	v_cvt_pk_bf16_f32 v60, v60, v61
	v_cvt_pk_bf16_f32 v61, v58, v59
	global_store_dwordx2 v[66:67], v[56:57], off offset:96
	v_lshlrev_b64 v[56:57], 6, v[54:55]
	global_store_dwordx2 v[66:67], v[72:73], off
	global_store_dwordx2 v[66:67], v[64:65], off offset:32
	global_store_dwordx2 v[66:67], v[60:61], off offset:64
	v_lshl_add_u64 v[70:71], s[90:91], 0, v[56:57]
	v_mov_b32_e32 v2, v109
	v_pk_mul_f32 v[48:49], v[48:49], v[2:3] op_sel_hi:[1,0]
	v_pk_mul_f32 v[50:51], v[50:51], v[2:3] op_sel_hi:[1,0]
	v_pk_mul_f32 v[36:37], v[36:37], v[2:3] op_sel_hi:[1,0]
	v_pk_mul_f32 v[38:39], v[38:39], v[2:3] op_sel_hi:[1,0]
	v_mad_i64_i32 v[54:55], s[0:1], v54, s34, v[0:1]
	v_pk_mul_f32 v[44:45], v[44:45], v[2:3] op_sel_hi:[1,0]
	v_cvt_pk_bf16_f32 v48, v48, v49
	v_cvt_pk_bf16_f32 v49, v50, v51
	v_lshl_add_u64 v[50:51], v[54:55], 0, v[52:53]
	v_cvt_pk_bf16_f32 v36, v36, v37
	v_cvt_pk_bf16_f32 v37, v38, v39
	v_pk_mul_f32 v[46:47], v[46:47], v[2:3] op_sel_hi:[1,0]
	global_store_dwordx2 v[50:51], v[36:37], off offset:64
	v_cvt_pk_bf16_f32 v36, v44, v45
	v_or_b32_e32 v44, 32, v68
	v_pk_mul_f32 v[40:41], v[40:41], v[2:3] op_sel_hi:[1,0]
	v_pk_mul_f32 v[42:43], v[42:43], v[2:3] op_sel_hi:[1,0]
	v_cvt_pk_bf16_f32 v37, v46, v47
	v_ashrrev_i32_e32 v45, 31, v44
	v_cvt_pk_bf16_f32 v40, v40, v41
	v_cvt_pk_bf16_f32 v41, v42, v43
	global_store_dwordx2 v[50:51], v[36:37], off offset:96
	v_lshlrev_b64 v[36:37], 6, v[44:45]
	global_store_dwordx2 v[50:51], v[48:49], off
	global_store_dwordx2 v[50:51], v[40:41], off offset:32
	v_lshl_add_u64 v[50:51], s[90:91], 0, v[36:37]
	v_mov_b32_e32 v2, v110
	v_pk_mul_f32 v[32:33], v[32:33], v[2:3] op_sel_hi:[1,0]
	v_pk_mul_f32 v[34:35], v[34:35], v[2:3] op_sel_hi:[1,0]
	v_pk_mul_f32 v[28:29], v[28:29], v[2:3] op_sel_hi:[1,0]
	v_pk_mul_f32 v[30:31], v[30:31], v[2:3] op_sel_hi:[1,0]
	v_mad_i64_i32 v[36:37], s[0:1], v44, s34, v[0:1]
	v_cvt_pk_bf16_f32 v32, v32, v33
	v_cvt_pk_bf16_f32 v33, v34, v35
	v_lshl_add_u64 v[34:35], v[36:37], 0, v[52:53]
	v_cvt_pk_bf16_f32 v28, v28, v29
	v_cvt_pk_bf16_f32 v29, v30, v31
	v_pk_mul_f32 v[20:21], v[20:21], v[2:3] op_sel_hi:[1,0]
	v_pk_mul_f32 v[22:23], v[22:23], v[2:3] op_sel_hi:[1,0]
	global_store_dwordx2 v[34:35], v[28:29], off offset:32
	v_or_b32_e32 v28, 48, v68
	v_pk_mul_f32 v[24:25], v[24:25], v[2:3] op_sel_hi:[1,0]
	v_pk_mul_f32 v[26:27], v[26:27], v[2:3] op_sel_hi:[1,0]
	v_cvt_pk_bf16_f32 v20, v20, v21
	v_cvt_pk_bf16_f32 v21, v22, v23
	v_ashrrev_i32_e32 v29, 31, v28
	v_cvt_pk_bf16_f32 v24, v24, v25
	v_cvt_pk_bf16_f32 v25, v26, v27
	global_store_dwordx2 v[34:35], v[20:21], off offset:96
	v_lshlrev_b64 v[20:21], 6, v[28:29]
	global_store_dwordx2 v[34:35], v[32:33], off
	global_store_dwordx2 v[34:35], v[24:25], off offset:64
	v_lshl_add_u64 v[34:35], s[90:91], 0, v[20:21]
	v_mad_i64_i32 v[0:1], s[0:1], v28, s34, v[0:1]
	v_lshl_add_u64 v[0:1], v[0:1], 0, v[52:53]
	s_mov_b64 s[0:1], 0x60
	v_mov_b32_e32 v2, v111
	v_pk_mul_f32 v[16:17], v[16:17], v[2:3] op_sel_hi:[1,0]
	v_pk_mul_f32 v[18:19], v[18:19], v[2:3] op_sel_hi:[1,0]
	v_pk_mul_f32 v[12:13], v[12:13], v[2:3] op_sel_hi:[1,0]
	v_pk_mul_f32 v[14:15], v[14:15], v[2:3] op_sel_hi:[1,0]
	v_pk_mul_f32 v[20:21], v[4:5], v[2:3] op_sel_hi:[1,0]
	v_pk_mul_f32 v[4:5], v[6:7], v[2:3] op_sel_hi:[1,0]
	v_cvt_pk_bf16_f32 v6, v16, v17
	v_cvt_pk_bf16_f32 v7, v18, v19
	v_pk_mul_f32 v[8:9], v[8:9], v[2:3] op_sel_hi:[1,0]
	v_pk_mul_f32 v[10:11], v[10:11], v[2:3] op_sel_hi:[1,0]
	global_store_dwordx2 v[0:1], v[6:7], off
	v_cvt_pk_bf16_f32 v6, v12, v13
	v_cvt_pk_bf16_f32 v7, v14, v15
	global_store_dwordx2 v[0:1], v[6:7], off offset:32
	v_cvt_pk_bf16_f32 v6, v8, v9
	v_cvt_pk_bf16_f32 v7, v10, v11
	global_store_dwordx2 v[0:1], v[6:7], off offset:64
	v_cvt_pk_bf16_f32 v2, v20, v21
	v_lshl_add_u64 v[6:7], v[0:1], 0, s[0:1]
	s_mov_b64 s[0:1], 0
	global_store_dword v[0:1], v2, off offset:96

; template <int MODE, bool SWAP, int MT>
; DI void gemm_tile(const int wv_, const Params& p, const u16* __restrict__ A, const u16* __restrict__ Bt, int brow, int bcol, char* smem, const float* gnext) {
;     ...
;   f32x4 acc[MT][4];
; #pragma unroll
;   for (int m = 0; m < MT; ++m)
; #pragma unroll
;     for (int n = 0; n < 4; ++n) acc[m][n] = f32x4{0.f, 0.f, 0.f, 0.f};
;   const int ra = tid >> 2, cb = (tid & 3) * 8;
;   const u16* ga0 = A + (size_t)(brow + ra) * 1024 + cb;
;   const u16* ga1 = A + (size_t)(brow + 128 + ra) * 1024 + cb;
;   const u16* gb0 = Bt + (size_t)(bcol + ra) * 1024 + cb;
;   auto stage = [&](int t, int buf) {
;     char* sA = smem + buf * 24576; char* sB = sA + 16384;
;     if (MT >= 2 || tid < 256) __builtin_amdgcn_global_load_lds((const unsigned*)(ga0 + t * 32), (unsigned*)(sA + tid * 16), 16, 0, 0);
;     if (MT == 4) __builtin_amdgcn_global_load_lds((const unsigned*)(ga1 + t * 32), (unsigned*)(sA + 8192 + tid * 16), 16, 0, 0);
;     __builtin_amdgcn_global_load_lds((const unsigned*)(gb0 + t * 32), (unsigned*)(sB + tid * 16), 16, 0, 0);
;   };
;   stage(0, 0);
.LBB0_372:
	s_mul_hi_i32 s0, s22, 0x3e0f83e1
	s_mov_b32 s7, 0
	s_lshr_b32 s1, s0, 31
	s_ashr_i32 s0, s0, 3
	s_add_i32 s6, s0, s1
	v_mbcnt_lo_u32_b32 v0, -1, s7
	v_mbcnt_hi_u32_b32 v0, -1, v0
	s_mul_i32 s0, s6, 0xffffffdf
	v_add_u32_e32 v2, s33, v0
	s_add_i32 s1, s0, s22
	s_lshl_b32 s0, s6, 8
	s_mov_b32 s7, s16
	v_ashrrev_i32_e32 v12, 2, v2
	v_add_u32_e32 v0, s0, v12
	s_mov_b32 s7, s17
	v_ashrrev_i32_e32 v1, 31, v0
	v_readlane_b32 s8, v127, 0
	v_lshlrev_b64 v[4:5], 11, v[0:1]
	v_readlane_b32 s9, v127, 1
	v_lshlrev_b32_e32 v76, 4, v2
	v_bfe_u32 v72, v2, 6, 1
	v_ashrrev_i32_e32 v74, 7, v2
	v_and_b32_e32 v75, 15, v2
	v_bfe_u32 v73, v2, 4, 2
	v_lshl_add_u64 v[6:7], s[8:9], 0, v[4:5]
	v_and_b32_e32 v2, 48, v76
	v_add_u32_e32 v0, 0x80, v0
	v_readfirstlane_b32 s7, v76
	v_lshl_add_u64 v[6:7], v[6:7], 0, v[2:3]
	v_ashrrev_i32_e32 v1, 31, v0
	s_mov_b32 m0, s7
	s_lshl_b32 s23, s1, 7
	v_lshlrev_b64 v[8:9], 11, v[0:1]
	global_load_lds_dwordx4 v[6:7], off
	v_add_u32_e32 v6, 0x2000, v76
	v_lshl_add_u64 v[0:1], s[8:9], 0, v[8:9]
	v_add_u32_e32 v10, s23, v12
	v_readfirstlane_b32 s7, v6
	v_lshl_add_u64 v[0:1], v[0:1], 0, v[2:3]
	v_ashrrev_i32_e32 v11, 31, v10
	s_mov_b32 m0, s7
	v_lshlrev_b64 v[10:11], 11, v[10:11]
	global_load_lds_dwordx4 v[0:1], off
	v_add_u32_e32 v0, 0x4000, v76
	v_lshl_add_u64 v[10:11], s[2:3], 0, v[10:11]
	v_readfirstlane_b32 s7, v0
	v_lshl_add_u64 v[10:11], v[10:11], 0, v[2:3]
	s_mov_b32 m0, s7
	v_readlane_b32 s8, v127, 22
	global_load_lds_dwordx4 v[10:11], off
	v_lshlrev_b32_e32 v0, 6, v75
	v_or_b32_e32 v4, v4, v2
	v_readlane_b32 s9, v127, 23
	v_lshl_or_b32 v78, v72, 12, v0
	v_lshl_or_b32 v79, v74, 12, v0
	v_lshl_add_u64 v[0:1], s[8:9], 0, v[4:5]
	v_add_u32_e32 v4, s20, v12
	s_mulk_i32 s6, 0x1080
	v_subrev_u32_e32 v4, s6, v4
	v_ashrrev_i32_e32 v5, 31, v4
	v_lshlrev_b64 v[4:5], 11, v[4:5]
	v_or_b32_e32 v4, v4, v2
	v_or_b32_e32 v8, v8, v2
	v_lshl_add_u64 v[70:71], s[4:5], 0, v[4:5]
	v_mov_b32_e32 v4, 0
	s_mov_b32 s1, 0
	v_lshlrev_b32_e32 v77, 4, v73
	v_lshl_add_u64 v[68:69], s[8:9], 0, v[8:9]
	v_mov_b32_e32 v5, v4
	v_mov_b32_e32 v6, v4
	v_mov_b32_e32 v7, v4
	v_mov_b32_e32 v8, v4
	v_mov_b32_e32 v9, v4
	v_mov_b32_e32 v10, v4
	v_mov_b32_e32 v11, v4
	v_mov_b32_e32 v12, v4
	v_mov_b32_e32 v13, v4
	v_mov_b32_e32 v14, v4
	v_mov_b32_e32 v15, v4
	v_mov_b32_e32 v16, v4
	v_mov_b32_e32 v17, v4
	v_mov_b32_e32 v18, v4
	v_mov_b32_e32 v19, v4
	v_mov_b32_e32 v20, v4
	v_mov_b32_e32 v21, v4
	v_mov_b32_e32 v22, v4
	v_mov_b32_e32 v23, v4
	v_mov_b32_e32 v24, v4
	v_mov_b32_e32 v25, v4
	v_mov_b32_e32 v26, v4
	v_mov_b32_e32 v27, v4
	v_mov_b32_e32 v28, v4
	v_mov_b32_e32 v29, v4
	v_mov_b32_e32 v30, v4
	v_mov_b32_e32 v31, v4
	v_mov_b32_e32 v32, v4
	v_mov_b32_e32 v33, v4
	v_mov_b32_e32 v34, v4
	v_mov_b32_e32 v35, v4
	v_mov_b32_e32 v44, v4
	v_mov_b32_e32 v45, v4
	v_mov_b32_e32 v46, v4
	v_mov_b32_e32 v47, v4
	v_mov_b32_e32 v36, v4
	v_mov_b32_e32 v37, v4
	v_mov_b32_e32 v38, v4
	v_mov_b32_e32 v39, v4
	v_mov_b32_e32 v40, v4
	v_mov_b32_e32 v41, v4
	v_mov_b32_e32 v42, v4
	v_mov_b32_e32 v43, v4
	v_mov_b32_e32 v48, v4
	v_mov_b32_e32 v49, v4
	v_mov_b32_e32 v50, v4
	v_mov_b32_e32 v51, v4
	v_mov_b32_e32 v52, v4
	v_mov_b32_e32 v53, v4
	v_mov_b32_e32 v54, v4
	v_mov_b32_e32 v55, v4
	v_mov_b32_e32 v56, v4
	v_mov_b32_e32 v57, v4
	v_mov_b32_e32 v58, v4
	v_mov_b32_e32 v59, v4
	v_mov_b32_e32 v60, v4
	v_mov_b32_e32 v61, v4
	v_mov_b32_e32 v62, v4
	v_mov_b32_e32 v63, v4
	v_mov_b32_e32 v64, v4
	v_mov_b32_e32 v65, v4
	v_mov_b32_e32 v66, v4
	v_mov_b32_e32 v67, v4
	v_readlane_b32 s10, v127, 2
	v_readlane_b32 s11, v127, 3
	v_or_b32_e32 v112, s0, v75
	v_lshl_add_u32 v112, v74, 6, v112
	v_lshlrev_b32_e32 v112, 6, v112
	global_load_dwordx4 v[4:7], v112, s[90:91]
	global_load_dwordx4 v[8:11], v112, s[90:91] offset:16
	global_load_dwordx4 v[12:15], v112, s[90:91] offset:32
	global_load_dwordx4 v[16:19], v112, s[90:91] offset:48
	global_load_dwordx4 v[20:23], v112, s[90:91] offset:1024
	global_load_dwordx4 v[24:27], v112, s[90:91] offset:1040
	global_load_dwordx4 v[28:31], v112, s[90:91] offset:1056
	global_load_dwordx4 v[32:35], v112, s[90:91] offset:1072
	global_load_dwordx4 v[36:39], v112, s[90:91] offset:2048
	global_load_dwordx4 v[40:43], v112, s[90:91] offset:2064
	global_load_dwordx4 v[44:47], v112, s[90:91] offset:2080
	global_load_dwordx4 v[48:51], v112, s[90:91] offset:2096
	global_load_dwordx4 v[52:55], v112, s[90:91] offset:3072
	global_load_dwordx4 v[56:59], v112, s[90:91] offset:3088
	global_load_dwordx4 v[60:63], v112, s[90:91] offset:3104
	global_load_dwordx4 v[64:67], v112, s[90:91] offset:3120
	v_mov_b32_e32 v113, 0x358637bd
	s_waitcnt vmcnt(0)
; DI float rowscale(const float* ss, int R) {
;   const float4* q = (const float4*)(ss + (size_t)R * 16);
;   float4 a = q[0], b = q[1], c = q[2], d = q[3];
;   float t = ((a.x + a.y) + (a.z + a.w)) + ((b.x + b.y) + (b.z + b.w)) + ((c.x + c.y) + (c.z + c.w)) + ((d.x + d.y) + (d.z + d.w));
;   return rsqrtf(t * (1.f / 1024.f) + 1e-6f);
; }
; template <int MODE, bool SWAP, int MT>
; DI void gemm_tile(const int wv_, const Params& p, const u16* __restrict__ A, const u16* __restrict__ Bt, int brow, int bcol, char* smem, const float* gnext) {
;   PHASE_IDS
;   const int tid = tid_, wid = tid >> 6, lane = tid & 63, wr = wid >> 1, wc = wid & 1, fr = lane & 15, fq = lane >> 4;
;   f32x4 acc[MT][4];
; #pragma unroll
;   for (int m = 0; m < MT; ++m)
; #pragma unroll
;     for (int n = 0; n < 4; ++n) acc[m][n] = f32x4{0.f, 0.f, 0.f, 0.f};
	v_add_f32_e32 v108, v4, v5
	v_add_f32_e32 v108, v108, v6
	v_add_f32_e32 v108, v108, v7
	v_add_f32_e32 v108, v108, v8
	v_add_f32_e32 v108, v108, v9
	v_add_f32_e32 v108, v108, v10
	v_add_f32_e32 v108, v108, v11
	v_add_f32_e32 v108, v108, v12
	v_add_f32_e32 v108, v108, v13
	v_add_f32_e32 v108, v108, v14
	v_add_f32_e32 v108, v108, v15
	v_add_f32_e32 v108, v108, v16
	v_add_f32_e32 v108, v108, v17
	v_add_f32_e32 v108, v108, v18
	v_add_f32_e32 v108, v108, v19
	v_fmamk_f32 v108, v108, 0x3a800000, v113
	v_cmp_gt_f32_e32 vcc, s96, v108
	v_mul_f32_e32 v114, 0x4b800000, v108
	s_nop 0
	v_cndmask_b32_e32 v108, v108, v114, vcc
	v_rsq_f32_e32 v108, v108
	s_nop 0
	v_mul_f32_e32 v114, 0x45800000, v108
	v_cndmask_b32_e32 v108, v108, v114, vcc
	v_add_f32_e32 v109, v20, v21
	v_add_f32_e32 v109, v109, v22
	v_add_f32_e32 v109, v109, v23
	v_add_f32_e32 v109, v109, v24
	v_add_f32_e32 v109, v109, v25
	v_add_f32_e32 v109, v109, v26
	v_add_f32_e32 v109, v109, v27
	v_add_f32_e32 v109, v109, v28
	v_add_f32_e32 v109, v109, v29
	v_add_f32_e32 v109, v109, v30
	v_add_f32_e32 v109, v109, v31
	v_add_f32_e32 v109, v109, v32
	v_add_f32_e32 v109, v109, v33
	v_add_f32_e32 v109, v109, v34
	v_add_f32_e32 v109, v109, v35
	v_fmamk_f32 v109, v109, 0x3a800000, v113
	v_cmp_gt_f32_e32 vcc, s96, v109
	v_mul_f32_e32 v114, 0x4b800000, v109
	s_nop 0
	v_cndmask_b32_e32 v109, v109, v114, vcc
	v_rsq_f32_e32 v109, v109
	s_nop 0
	v_mul_f32_e32 v114, 0x45800000, v109
	v_cndmask_b32_e32 v109, v109, v114, vcc
	v_add_f32_e32 v110, v36, v37
	v_add_f32_e32 v110, v110, v38
	v_add_f32_e32 v110, v110, v39
	v_add_f32_e32 v110, v110, v40
	v_add_f32_e32 v110, v110, v41
	v_add_f32_e32 v110, v110, v42
	v_add_f32_e32 v110, v110, v43
	v_add_f32_e32 v110, v110, v44
	v_add_f32_e32 v110, v110, v45
	v_add_f32_e32 v110, v110, v46
	v_add_f32_e32 v110, v110, v47
	v_add_f32_e32 v110, v110, v48
	v_add_f32_e32 v110, v110, v49
	v_add_f32_e32 v110, v110, v50
	v_add_f32_e32 v110, v110, v51
	v_fmamk_f32 v110, v110, 0x3a800000, v113
	v_cmp_gt_f32_e32 vcc, s96, v110
	v_mul_f32_e32 v114, 0x4b800000, v110
	s_nop 0
	v_cndmask_b32_e32 v110, v110, v114, vcc
	v_rsq_f32_e32 v110, v110
	s_nop 0
	v_mul_f32_e32 v114, 0x45800000, v110
	v_cndmask_b32_e32 v110, v110, v114, vcc
	v_add_f32_e32 v111, v52, v53
	v_add_f32_e32 v111, v111, v54
	v_add_f32_e32 v111, v111, v55
	v_add_f32_e32 v111, v111, v56
	v_add_f32_e32 v111, v111, v57
	v_add_f32_e32 v111, v111, v58
	v_add_f32_e32 v111, v111, v59
	v_add_f32_e32 v111, v111, v60
	v_add_f32_e32 v111, v111, v61
	v_add_f32_e32 v111, v111, v62
	v_add_f32_e32 v111, v111, v63
	v_add_f32_e32 v111, v111, v64
	v_add_f32_e32 v111, v111, v65
	v_add_f32_e32 v111, v111, v66
	v_add_f32_e32 v111, v111, v67
	v_fmamk_f32 v111, v111, 0x3a800000, v113
	v_cmp_gt_f32_e32 vcc, s96, v111
	v_mul_f32_e32 v114, 0x4b800000, v111
	s_nop 0
	v_cndmask_b32_e32 v111, v111, v114, vcc
	v_rsq_f32_e32 v111, v111
	s_nop 0
	v_mul_f32_e32 v114, 0x45800000, v111
	v_cndmask_b32_e32 v111, v111, v114, vcc
	v_mov_b32_e32 v4, 0
	v_mov_b32_e32 v5, 0
	v_mov_b32_e32 v6, 0
	v_mov_b32_e32 v7, 0
	v_mov_b32_e32 v8, 0
	v_mov_b32_e32 v9, 0
	v_mov_b32_e32 v10, 0
	v_mov_b32_e32 v11, 0
	v_mov_b32_e32 v12, 0
	v_mov_b32_e32 v13, 0
	v_mov_b32_e32 v14, 0
	v_mov_b32_e32 v15, 0
	v_mov_b32_e32 v16, 0
	v_mov_b32_e32 v17, 0
	v_mov_b32_e32 v18, 0
	v_mov_b32_e32 v19, 0
	v_mov_b32_e32 v20, 0
	v_mov_b32_e32 v21, 0
	v_mov_b32_e32 v22, 0
	v_mov_b32_e32 v23, 0
	v_mov_b32_e32 v24, 0
	v_mov_b32_e32 v25, 0
	v_mov_b32_e32 v26, 0
	v_mov_b32_e32 v27, 0
	v_mov_b32_e32 v28, 0
	v_mov_b32_e32 v29, 0
	v_mov_b32_e32 v30, 0
	v_mov_b32_e32 v31, 0
	v_mov_b32_e32 v32, 0
	v_mov_b32_e32 v33, 0
	v_mov_b32_e32 v34, 0
	v_mov_b32_e32 v35, 0
	v_mov_b32_e32 v36, 0
	v_mov_b32_e32 v37, 0
	v_mov_b32_e32 v38, 0
	v_mov_b32_e32 v39, 0
	v_mov_b32_e32 v40, 0
	v_mov_b32_e32 v41, 0
	v_mov_b32_e32 v42, 0
	v_mov_b32_e32 v43, 0
	v_mov_b32_e32 v44, 0
	v_mov_b32_e32 v45, 0
	v_mov_b32_e32 v46, 0
	v_mov_b32_e32 v47, 0
	v_mov_b32_e32 v48, 0
	v_mov_b32_e32 v49, 0
	v_mov_b32_e32 v50, 0
	v_mov_b32_e32 v51, 0
	v_mov_b32_e32 v52, 0
	v_mov_b32_e32 v53, 0
	v_mov_b32_e32 v54, 0
	v_mov_b32_e32 v55, 0
	v_mov_b32_e32 v56, 0
	v_mov_b32_e32 v57, 0
	v_mov_b32_e32 v58, 0
	v_mov_b32_e32 v59, 0
	v_mov_b32_e32 v60, 0
	v_mov_b32_e32 v61, 0
	v_mov_b32_e32 v62, 0
	v_mov_b32_e32 v63, 0
	v_mov_b32_e32 v64, 0
	v_mov_b32_e32 v65, 0
	v_mov_b32_e32 v66, 0
	v_mov_b32_e32 v67, 0
; template <int MODE, bool SWAP, int MT>
; DI void gemm_tile(const int wv_, const Params& p, const u16* __restrict__ A, const u16* __restrict__ Bt, int brow, int bcol, char* smem, const float* gnext) {
;     ...
;   for (int t = 0; t < 32; ++t) {
;     asm volatile("s_waitcnt vmcnt(0)" ::: "memory");
;     __syncthreads();
;     if (t + 1 < 32) stage(t + 1, (t + 1) & 1);
;     const char* sA = smem + (t & 1) * 24576; const char* sB = sA + 16384;
;     bf16x8 Af[MT], Bf[4];
; #pragma unroll
;     for (int n = 0; n < 4; ++n) Bf[n] = *(const bf16x8*)(sB + (wc * 64 + n * 16 + fr) * 64 + fq * 16);
;     constexpr int MH = MT >= 2 ? MT / 2 : 1;
; #pragma unroll
;     for (int m = 0; m < MH; ++m) Af[m] = *(const bf16x8*)(sA + (wr * (16 * MT) + m * 16 + fr) * 64 + fq * 16);
;     __builtin_amdgcn_sched_barrier(0);
; #pragma unroll
;     for (int m = MH; m < MT; ++m) Af[m] = *(const bf16x8*)(sA + (wr * (16 * MT) + m * 16 + fr) * 64 + fq * 16);
; #pragma unroll
;     for (int m = 0; m < MH; ++m)
; #pragma unroll
;       for (int n = 0; n < 4; ++n)
;         acc[m][n] = SWAP ? __builtin_amdgcn_mfma_f32_16x16x32_bf16(Bf[n], Af[m], acc[m][n], 0, 0, 0)
;                          : __builtin_amdgcn_mfma_f32_16x16x32_bf16(Af[m], Bf[n], acc[m][n], 0, 0, 0);
;     __builtin_amdgcn_sched_barrier(0);
; #pragma unroll
;     for (int m = MH; m < MT; ++m)
; #pragma unroll
;       for (int n = 0; n < 4; ++n)
;         acc[m][n] = SWAP ? __builtin_amdgcn_mfma_f32_16x16x32_bf16(Bf[n], Af[m], acc[m][n], 0, 0, 0)
;                          : __builtin_amdgcn_mfma_f32_16x16x32_bf16(Af[m], Bf[n], acc[m][n], 0, 0, 0);
;   }
;     ...
;         const float rs = rowscale(p.ss, R);
; #pragma unroll
;         for (int n = 0; n < 4; ++n) { acc[m][n][0] *= rs; acc[m][n][1] *= rs; acc[m][n][2] *= rs; acc[m][n][3] *= rs; }
;         if (MODE == 0 && bcol >= 512 && bcol < 1536) {
;           int b = R / P, pos = R - b * P;
;           u16* dstb = (bcol < 1024 ? p.kc : p.vc);
; #pragma unroll
;           for (int n = 0; n < 4; ++n) {
;             int cc = (bcol & 511) + wc * 64 + n * 16 + fq * 4;
;             uint2 o; o.x = pack2(acc[m][n][0], acc[m][n][1]); o.y = pack2(acc[m][n][2], acc[m][n][3]);
;             *(uint2*)(dstb + ((size_t)((b * 8 + (cc >> 6)) * P + pos)) * 64 + (cc & 63)) = o;
;           }
;         } else {
;           const int LD = MODE == 0 ? LD_AB : LD_CD;
.LBB0_373:
	s_add_i32 s6, s1, 1
	s_bitcmp1_b32 s6, 0
	s_cselect_b32 s7, 0x6000, 0
	v_add_u32_e32 v2, s7, v76
	v_add_u32_e32 v80, 0x2000, v2
	v_readfirstlane_b32 s7, v2
	s_mov_b32 m0, s7
	v_readfirstlane_b32 s7, v80
	v_add_u32_e32 v2, 0x4000, v2
	s_waitcnt vmcnt(0)
	s_waitcnt vmcnt(0) lgkmcnt(0)
	s_barrier
	global_load_lds_dwordx4 v[0:1], off
	s_mov_b32 m0, s7
	v_readfirstlane_b32 s7, v2
	global_load_lds_dwordx4 v[68:69], off
	s_mov_b32 m0, s7
	s_bitcmp1_b32 s1, 0
	global_load_lds_dwordx4 v[70:71], off
	s_cselect_b32 s1, 0x6000, 0
	v_or_b32_e32 v2, s1, v77
	v_add_u32_e32 v92, v2, v78
	ds_read_b128 v[80:83], v92 offset:16384
	ds_read_b128 v[84:87], v92 offset:17408
	ds_read_b128 v[88:91], v92 offset:18432
	ds_read_b128 v[92:95], v92 offset:19456
	v_add_u32_e32 v2, v2, v79
	ds_read_b128 v[96:99], v2
	ds_read_b128 v[100:103], v2 offset:1024
	s_waitcnt lgkmcnt(0)
	v_mfma_f32_16x16x32_bf16 v[64:67], v[80:83], v[96:99], v[64:67]
	v_mfma_f32_16x16x32_bf16 v[60:63], v[84:87], v[96:99], v[60:63]
	v_mfma_f32_16x16x32_bf16 v[56:59], v[88:91], v[96:99], v[56:59]
	v_mfma_f32_16x16x32_bf16 v[52:55], v[92:95], v[96:99], v[52:55]
	ds_read_b128 v[96:99], v2 offset:2048
	ds_read_b128 v[104:107], v2 offset:3072
	v_mfma_f32_16x16x32_bf16 v[48:51], v[80:83], v[100:103], v[48:51]
	v_mfma_f32_16x16x32_bf16 v[40:43], v[84:87], v[100:103], v[40:43]
	v_mfma_f32_16x16x32_bf16 v[36:39], v[88:91], v[100:103], v[36:39]
	v_mfma_f32_16x16x32_bf16 v[44:47], v[92:95], v[100:103], v[44:47]
	s_waitcnt lgkmcnt(0)
	v_mfma_f32_16x16x32_bf16 v[32:35], v[80:83], v[96:99], v[32:35]
	v_lshl_add_u64 v[0:1], v[0:1], 0, 64
	v_lshl_add_u64 v[68:69], v[68:69], 0, 64
	v_lshl_add_u64 v[70:71], v[70:71], 0, 64
	v_mfma_f32_16x16x32_bf16 v[28:31], v[84:87], v[96:99], v[28:31]
	s_cmp_eq_u32 s6, 31
	s_mov_b32 s1, s6
	v_mfma_f32_16x16x32_bf16 v[24:27], v[88:91], v[96:99], v[24:27]
	v_mfma_f32_16x16x32_bf16 v[20:23], v[92:95], v[96:99], v[20:23]
	v_mfma_f32_16x16x32_bf16 v[16:19], v[80:83], v[104:107], v[16:19]
	v_mfma_f32_16x16x32_bf16 v[12:15], v[84:87], v[104:107], v[12:15]
	v_mfma_f32_16x16x32_bf16 v[8:11], v[88:91], v[104:107], v[8:11]
	v_mfma_f32_16x16x32_bf16 v[4:7], v[92:95], v[104:107], v[4:7]
	s_cbranch_scc0 .LBB0_373
	v_add_u32_e32 v0, v77, v79
	v_add_u32_e32 v1, v77, v78
	s_waitcnt vmcnt(0)
	s_waitcnt vmcnt(0)
	s_barrier
	ds_read_b128 v[68:71], v0 offset:25600
	ds_read_b128 v[80:83], v0 offset:24576
	ds_read_b128 v[76:79], v1 offset:44032
	ds_read_b128 v[84:87], v1 offset:43008
	ds_read_b128 v[88:91], v1 offset:41984
	ds_read_b128 v[92:95], v1 offset:40960
	s_waitcnt lgkmcnt(0)
	v_mfma_f32_16x16x32_bf16 v[64:67], v[92:95], v[80:83], v[64:67]
	v_mfma_f32_16x16x32_bf16 v[60:63], v[88:91], v[80:83], v[60:63]
	v_mfma_f32_16x16x32_bf16 v[56:59], v[84:87], v[80:83], v[56:59]
	v_mfma_f32_16x16x32_bf16 v[52:55], v[76:79], v[80:83], v[52:55]
	ds_read_b128 v[80:83], v0 offset:26624
	ds_read_b128 v[96:99], v0 offset:27648
	v_mfma_f32_16x16x32_bf16 v[48:51], v[92:95], v[68:71], v[48:51]
	v_mfma_f32_16x16x32_bf16 v[40:43], v[88:91], v[68:71], v[40:43]
	v_mfma_f32_16x16x32_bf16 v[36:39], v[84:87], v[68:71], v[36:39]
	v_mfma_f32_16x16x32_bf16 v[44:47], v[76:79], v[68:71], v[44:47]
	v_or_b32_e32 v0, s0, v75
	v_lshl_add_u32 v68, v74, 6, v0
	v_ashrrev_i32_e32 v69, 31, v68
	v_lshlrev_b64 v[70:71], 6, v[68:69]
	v_lshl_add_u64 v[74:75], s[90:91], 0, v[70:71]
	s_waitcnt lgkmcnt(1)
	v_mfma_f32_16x16x32_bf16 v[32:35], v[92:95], v[80:83], v[32:35]
	s_waitcnt lgkmcnt(0)
	s_barrier
	v_mfma_f32_16x16x32_bf16 v[28:31], v[88:91], v[80:83], v[28:31]
	v_lshlrev_b32_e32 v2, 2, v73
	s_add_i32 s0, s23, 0xfffffe00
	s_cmpk_gt_u32 s0, 0x3ff
	v_mfma_f32_16x16x32_bf16 v[24:27], v[84:87], v[80:83], v[24:27]
	s_cselect_b64 s[8:9], -1, 0
	s_cmpk_lt_u32 s23, 0x400
	s_movk_i32 s0, 0x1058
	v_mfma_f32_16x16x32_bf16 v[20:23], v[76:79], v[80:83], v[20:23]
	s_cselect_b64 s[6:7], -1, 0
	s_mov_b64 s[10:11], -1
	v_mfma_f32_16x16x32_bf16 v[12:15], v[88:91], v[96:99], v[12:15]
	v_mfma_f32_16x16x32_bf16 v[8:11], v[84:87], v[96:99], v[8:11]
	v_mfma_f32_16x16x32_bf16 v[4:7], v[76:79], v[96:99], v[4:7]
	v_lshlrev_b32_e32 v77, 6, v72
	v_or_b32_e32 v76, s23, v77
	v_mfma_f32_16x16x32_bf16 v[16:19], v[92:95], v[96:99], v[16:19]
	v_or_b32_e32 v0, v76, v2
	v_cmp_gt_i32_e64 s[0:1], s0, v0
	v_mov_b32_e32 v72, v108
	v_pk_mul_f32 v[70:71], v[64:65], v[72:73] op_sel_hi:[1,0]
	v_pk_mul_f32 v[66:67], v[66:67], v[72:73] op_sel_hi:[1,0]
	v_pk_mul_f32 v[64:65], v[60:61], v[72:73] op_sel_hi:[1,0]
	v_pk_mul_f32 v[62:63], v[62:63], v[72:73] op_sel_hi:[1,0]
	v_pk_mul_f32 v[60:61], v[56:57], v[72:73] op_sel_hi:[1,0]
	v_pk_mul_f32 v[58:59], v[58:59], v[72:73] op_sel_hi:[1,0]
	v_pk_mul_f32 v[56:57], v[52:53], v[72:73] op_sel_hi:[1,0]
	v_pk_mul_f32 v[52:53], v[54:55], v[72:73] op_sel_hi:[1,0]
	s_and_b64 vcc, exec, s[8:9]
	s_cbranch_vccz .LBB0_388
	v_mov_b64_e32 v[54:55], s[68:69]
	v_mad_i64_i32 v[72:73], s[10:11], v68, s35, v[54:55]
	v_lshlrev_b64 v[54:55], 7, v[68:69]
	s_and_saveexec_b64 s[10:11], s[0:1]
	s_cbranch_execz .LBB0_378
	s_movk_i32 s0, 0x5ff
	v_add_u32_e32 v1, 0xfffffc00, v0
	v_cmp_lt_i32_e32 vcc, s0, v0
	s_movk_i32 s0, 0xa00
	v_cvt_pk_bf16_f32 v74, v70, v71
	v_cndmask_b32_e32 v78, v0, v1, vcc
	v_ashrrev_i32_e32 v79, 31, v78
	v_cvt_pk_bf16_f32 v75, v66, v67
	v_lshl_add_u64 v[78:79], v[78:79], 1, v[72:73]
	v_cmp_eq_u32_e32 vcc, s0, v76
	global_store_dwordx2 v[78:79], v[74:75], off
	s_and_b64 exec, exec, vcc
	s_cbranch_execz .LBB0_378
	v_lshl_add_u64 v[78:79], s[78:79], 0, v[54:55]
	v_mov_b32_e32 v1, v3
	v_lshl_add_u64 v[78:79], v[0:1], 1, v[78:79]
	v_add_co_u32_e32 v78, vcc, 0xfffff000, v78
	s_nop 1
	v_addc_co_u32_e32 v79, vcc, -1, v79, vcc
	global_store_dwordx2 v[78:79], v[74:75], off offset:-1024

; DI unsigned pack2(float a, float b) { f32x2_t v = {a, b}; return __builtin_bit_cast(unsigned, __builtin_convertvector(v, bf16x2_t)); }
; template <int MODE, bool SWAP, int MT>
; DI void gemm_tile(const int wv_, const Params& p, const u16* __restrict__ A, const u16* __restrict__ Bt, int brow, int bcol, char* smem, const float* gnext) {
;     ...
;         const float rs = rowscale(p.ss, R);
; #pragma unroll
;         for (int n = 0; n < 4; ++n) { acc[m][n][0] *= rs; acc[m][n][1] *= rs; acc[m][n][2] *= rs; acc[m][n][3] *= rs; }
;         if (MODE == 0 && bcol >= 512 && bcol < 1536) {
;           int b = R / P, pos = R - b * P;
;           u16* dstb = (bcol < 1024 ? p.kc : p.vc);
; #pragma unroll
;           for (int n = 0; n < 4; ++n) {
;             int cc = (bcol & 511) + wc * 64 + n * 16 + fq * 4;
;             uint2 o; o.x = pack2(acc[m][n][0], acc[m][n][1]); o.y = pack2(acc[m][n][2], acc[m][n][3]);
;             *(uint2*)(dstb + ((size_t)((b * 8 + (cc >> 6)) * P + pos)) * 64 + (cc & 63)) = o;
;           }
;         } else {
;           const int LD = MODE == 0 ? LD_AB : LD_CD;
;           u16* pr = p.proj + (size_t)R * LD;
; #pragma unroll
;           for (int n = 0; n < 4; ++n) {
;             int col = bcol + wc * 64 + n * 16 + fq * 4;
;             if (MODE == 1 || col < 4184) {
;               uint2 o; o.x = pack2(acc[m][n][0], acc[m][n][1]); o.y = pack2(acc[m][n][2], acc[m][n][3]);
;               int pcol = (MODE == 0 && col >= 1536) ? col - 1024 : col;
;               *(uint2*)(pr + pcol) = o;
;               if (MODE == 0 && col >= 2560 && col < 2624) *(uint2*)(p.ikc + (size_t)R * 64 + (col - 2560)) = o;
.LBB0_390:
	v_or_b32_e32 v52, 16, v68
	v_ashrrev_i32_e32 v53, 31, v52
	v_lshlrev_b64 v[54:55], 6, v[52:53]
	v_lshl_add_u64 v[66:67], s[90:91], 0, v[54:55]
	s_mov_b64 s[10:11], -1
	v_mov_b32_e32 v58, v109
	v_cndmask_b32_e64 v1, 0, 1, s[8:9]
	v_pk_mul_f32 v[56:57], v[48:49], v[58:59] op_sel_hi:[1,0]
	v_pk_mul_f32 v[54:55], v[50:51], v[58:59] op_sel_hi:[1,0]
	v_pk_mul_f32 v[50:51], v[40:41], v[58:59] op_sel_hi:[1,0]
	v_pk_mul_f32 v[48:49], v[42:43], v[58:59] op_sel_hi:[1,0]
	v_pk_mul_f32 v[42:43], v[36:37], v[58:59] op_sel_hi:[1,0]
	v_pk_mul_f32 v[40:41], v[38:39], v[58:59] op_sel_hi:[1,0]
	v_pk_mul_f32 v[38:39], v[44:45], v[58:59] op_sel_hi:[1,0]
	v_pk_mul_f32 v[36:37], v[46:47], v[58:59] op_sel_hi:[1,0]
	v_cmp_ne_u32_e64 s[0:1], 1, v1
	s_andn2_b64 vcc, exec, s[8:9]
	s_cbranch_vccnz .LBB0_404
	v_mov_b64_e32 v[44:45], s[68:69]
	v_mad_i64_i32 v[46:47], s[8:9], v52, s35, v[44:45]
	s_movk_i32 s8, 0x1058
	v_lshlrev_b64 v[44:45], 7, v[52:53]
	v_cmp_gt_i32_e32 vcc, s8, v0
	s_and_saveexec_b64 s[8:9], vcc
	s_cbranch_execz .LBB0_394
	s_movk_i32 s10, 0x5ff
	v_add_u32_e32 v1, 0xfffffc00, v0
	v_cmp_lt_i32_e32 vcc, s10, v0
	s_movk_i32 s10, 0xa00
	v_cvt_pk_bf16_f32 v58, v56, v57
	v_cndmask_b32_e32 v60, v0, v1, vcc
	v_ashrrev_i32_e32 v61, 31, v60
	v_cvt_pk_bf16_f32 v59, v54, v55
	v_lshl_add_u64 v[60:61], v[60:61], 1, v[46:47]
	v_cmp_eq_u32_e32 vcc, s10, v76
	global_store_dwordx2 v[60:61], v[58:59], off
	s_and_b64 exec, exec, vcc
	s_cbranch_execz .LBB0_394
	v_lshl_add_u64 v[60:61], s[78:79], 0, v[44:45]
	v_mov_b32_e32 v1, v3
	v_lshl_add_u64 v[60:61], v[0:1], 1, v[60:61]
	v_add_co_u32_e32 v60, vcc, 0xfffff000, v60
	s_nop 1
	v_addc_co_u32_e32 v61, vcc, -1, v61, vcc
	global_store_dwordx2 v[60:61], v[58:59], off offset:-1024

; DI unsigned pack2(float a, float b) { f32x2_t v = {a, b}; return __builtin_bit_cast(unsigned, __builtin_convertvector(v, bf16x2_t)); }
; template <int MODE, bool SWAP, int MT>
; DI void gemm_tile(const int wv_, const Params& p, const u16* __restrict__ A, const u16* __restrict__ Bt, int brow, int bcol, char* smem, const float* gnext) {
;     ...
;         const float rs = rowscale(p.ss, R);
; #pragma unroll
;         for (int n = 0; n < 4; ++n) { acc[m][n][0] *= rs; acc[m][n][1] *= rs; acc[m][n][2] *= rs; acc[m][n][3] *= rs; }
;         if (MODE == 0 && bcol >= 512 && bcol < 1536) {
;           int b = R / P, pos = R - b * P;
;           u16* dstb = (bcol < 1024 ? p.kc : p.vc);
; #pragma unroll
;           for (int n = 0; n < 4; ++n) {
;             int cc = (bcol & 511) + wc * 64 + n * 16 + fq * 4;
;             uint2 o; o.x = pack2(acc[m][n][0], acc[m][n][1]); o.y = pack2(acc[m][n][2], acc[m][n][3]);
;             *(uint2*)(dstb + ((size_t)((b * 8 + (cc >> 6)) * P + pos)) * 64 + (cc & 63)) = o;
;           }
;         } else {
;           const int LD = MODE == 0 ? LD_AB : LD_CD;
;           u16* pr = p.proj + (size_t)R * LD;
; #pragma unroll
;           for (int n = 0; n < 4; ++n) {
;             int col = bcol + wc * 64 + n * 16 + fq * 4;
;             if (MODE == 1 || col < 4184) {
;               uint2 o; o.x = pack2(acc[m][n][0], acc[m][n][1]); o.y = pack2(acc[m][n][2], acc[m][n][3]);
;               int pcol = (MODE == 0 && col >= 1536) ? col - 1024 : col;
;               *(uint2*)(pr + pcol) = o;
;               if (MODE == 0 && col >= 2560 && col < 2624) *(uint2*)(p.ikc + (size_t)R * 64 + (col - 2560)) = o;
.LBB0_406:
	v_or_b32_e32 v36, 32, v68
	v_ashrrev_i32_e32 v37, 31, v36
	v_lshlrev_b64 v[38:39], 6, v[36:37]
	v_lshl_add_u64 v[50:51], s[90:91], 0, v[38:39]
	s_mov_b64 s[8:9], -1
	v_mov_b32_e32 v40, v110
	v_pk_mul_f32 v[38:39], v[32:33], v[40:41] op_sel_hi:[1,0]
	v_pk_mul_f32 v[34:35], v[34:35], v[40:41] op_sel_hi:[1,0]
	v_pk_mul_f32 v[32:33], v[28:29], v[40:41] op_sel_hi:[1,0]
	v_pk_mul_f32 v[30:31], v[30:31], v[40:41] op_sel_hi:[1,0]
	v_pk_mul_f32 v[28:29], v[24:25], v[40:41] op_sel_hi:[1,0]
	v_pk_mul_f32 v[26:27], v[26:27], v[40:41] op_sel_hi:[1,0]
	v_pk_mul_f32 v[24:25], v[20:21], v[40:41] op_sel_hi:[1,0]
	v_pk_mul_f32 v[20:21], v[22:23], v[40:41] op_sel_hi:[1,0]
	s_and_b64 vcc, exec, s[0:1]
	s_cbranch_vccnz .LBB0_420
	v_mov_b64_e32 v[22:23], s[68:69]
	v_mad_i64_i32 v[40:41], s[8:9], v36, s35, v[22:23]
	s_movk_i32 s8, 0x1058
	v_lshlrev_b64 v[22:23], 7, v[36:37]
	v_cmp_gt_i32_e32 vcc, s8, v0
	s_and_saveexec_b64 s[8:9], vcc
	s_cbranch_execz .LBB0_410
	s_movk_i32 s10, 0x5ff
	v_add_u32_e32 v1, 0xfffffc00, v0
	v_cmp_lt_i32_e32 vcc, s10, v0
	s_movk_i32 s10, 0xa00
	v_cvt_pk_bf16_f32 v42, v38, v39
	v_cndmask_b32_e32 v44, v0, v1, vcc
	v_ashrrev_i32_e32 v45, 31, v44
	v_cvt_pk_bf16_f32 v43, v34, v35
	v_lshl_add_u64 v[44:45], v[44:45], 1, v[40:41]
	v_cmp_eq_u32_e32 vcc, s10, v76
	global_store_dwordx2 v[44:45], v[42:43], off
	s_and_b64 exec, exec, vcc
	s_cbranch_execz .LBB0_410
	v_lshl_add_u64 v[44:45], s[78:79], 0, v[22:23]
	v_mov_b32_e32 v1, v3
	v_lshl_add_u64 v[44:45], v[0:1], 1, v[44:45]
	v_add_co_u32_e32 v44, vcc, 0xfffff000, v44
	s_nop 1
	v_addc_co_u32_e32 v45, vcc, -1, v45, vcc
	global_store_dwordx2 v[44:45], v[42:43], off offset:-1024

; DI unsigned pack2(float a, float b) { f32x2_t v = {a, b}; return __builtin_bit_cast(unsigned, __builtin_convertvector(v, bf16x2_t)); }
; template <int MODE, bool SWAP, int MT>
; DI void gemm_tile(const int wv_, const Params& p, const u16* __restrict__ A, const u16* __restrict__ Bt, int brow, int bcol, char* smem, const float* gnext) {
;     ...
;         const float rs = rowscale(p.ss, R);
; #pragma unroll
;         for (int n = 0; n < 4; ++n) { acc[m][n][0] *= rs; acc[m][n][1] *= rs; acc[m][n][2] *= rs; acc[m][n][3] *= rs; }
;         if (MODE == 0 && bcol >= 512 && bcol < 1536) {
;           int b = R / P, pos = R - b * P;
;           u16* dstb = (bcol < 1024 ? p.kc : p.vc);
; #pragma unroll
;           for (int n = 0; n < 4; ++n) {
;             int cc = (bcol & 511) + wc * 64 + n * 16 + fq * 4;
;             uint2 o; o.x = pack2(acc[m][n][0], acc[m][n][1]); o.y = pack2(acc[m][n][2], acc[m][n][3]);
;             *(uint2*)(dstb + ((size_t)((b * 8 + (cc >> 6)) * P + pos)) * 64 + (cc & 63)) = o;
;           }
;         } else {
;           const int LD = MODE == 0 ? LD_AB : LD_CD;
;           u16* pr = p.proj + (size_t)R * LD;
; #pragma unroll
;           for (int n = 0; n < 4; ++n) {
;             int col = bcol + wc * 64 + n * 16 + fq * 4;
;             if (MODE == 1 || col < 4184) {
;               uint2 o; o.x = pack2(acc[m][n][0], acc[m][n][1]); o.y = pack2(acc[m][n][2], acc[m][n][3]);
;               int pcol = (MODE == 0 && col >= 1536) ? col - 1024 : col;
;               *(uint2*)(pr + pcol) = o;
;               if (MODE == 0 && col >= 2560 && col < 2624) *(uint2*)(p.ikc + (size_t)R * 64 + (col - 2560)) = o;
.LBB0_422:
	v_or_b32_e32 v20, 48, v68
	v_ashrrev_i32_e32 v21, 31, v20
	v_lshlrev_b64 v[22:23], 6, v[20:21]
	v_lshl_add_u64 v[34:35], s[90:91], 0, v[22:23]
	s_mov_b64 s[8:9], -1
	v_mov_b32_e32 v24, v111
	v_pk_mul_f32 v[22:23], v[16:17], v[24:25] op_sel_hi:[1,0]
	v_pk_mul_f32 v[18:19], v[18:19], v[24:25] op_sel_hi:[1,0]
	v_pk_mul_f32 v[16:17], v[12:13], v[24:25] op_sel_hi:[1,0]
	v_pk_mul_f32 v[14:15], v[14:15], v[24:25] op_sel_hi:[1,0]
	v_pk_mul_f32 v[12:13], v[8:9], v[24:25] op_sel_hi:[1,0]
	v_pk_mul_f32 v[10:11], v[10:11], v[24:25] op_sel_hi:[1,0]
	v_pk_mul_f32 v[8:9], v[4:5], v[24:25] op_sel_hi:[1,0]
	v_pk_mul_f32 v[4:5], v[6:7], v[24:25] op_sel_hi:[1,0]
	s_and_b64 vcc, exec, s[0:1]
	s_cbranch_vccz .LBB0_424
	s_and_b64 vcc, exec, s[8:9]
	s_cbranch_vccz .LBB0_371
	s_branch .LBB0_437
